# in-proj and merge gate-GEMM epilogues run at s_setprio 2 (reset at phase end / next k-loop), on top of v50
# baseline (speedup 1.0000x reference)
; DI void gemm_128_deep(const bf16_t* __restrict__ A, int lda, const bf16_t* __restrict__ B, int ldb, int K, f32x16 (&acc)[2][2], bf16_t* sA, bf16_t* sBunused) {
;     ...
;   GL_P(0)
;   GL_Q(64)
;   __syncthreads();
;   ST_LDS(0, pa0, pa1, pa2, pa3, pb0, pb1, pb2, pb3)
;   GL_P(128)
;   __syncthreads();
;   for (int k0 = 0; k0 < K - 256; k0 += 128) {
;     MMA_TILE(0)
;     ST_LDS(1, qa0, qa1, qa2, qa3, qb0, qb1, qb2, qb3)
;     GL_Q(k0 + 192)
;     __syncthreads();
;     MMA_TILE(1)
;     ST_LDS(0, pa0, pa1, pa2, pa3, pb0, pb1, pb2, pb3)
;     GL_P(k0 + 256)
;     __syncthreads();
;   }
.LBB0_208:
	ds_read_b128 v[168:171], v128
	ds_read_b128 v[172:175], v129 offset:18432
	ds_read_b128 v[176:179], v128 offset:32
	ds_read_b128 v[180:183], v129 offset:18464
	ds_read_b128 v[184:187], v129 offset:23040
	ds_read_b128 v[188:191], v129 offset:23072
	s_mov_b32 s45, 0x1304000
	s_waitcnt lgkmcnt(4)
	v_mfma_f32_32x32x16_bf16 v[48:63], v[168:171], v[172:175], v[48:63]
	s_mov_b32 s46, 0x1324000
	s_mov_b32 s47, 0x1344000
	s_mov_b32 s48, 0x1364000
	s_addk_i32 s43, 0x80
	s_cmpk_lt_u32 s43, 0x680
	s_waitcnt lgkmcnt(1)
	v_mfma_f32_32x32x16_bf16 v[32:47], v[168:171], v[184:187], v[32:47]
	ds_read_b128 v[168:171], v128 offset:4608
	ds_read_b128 v[192:195], v128 offset:4640
	s_waitcnt lgkmcnt(1)
	v_mfma_f32_32x32x16_bf16 v[16:31], v[168:171], v[172:175], v[16:31]
	v_mfma_f32_32x32x16_bf16 v[0:15], v[168:171], v[184:187], v[0:15]
	v_mfma_f32_32x32x16_bf16 v[48:63], v[176:179], v[180:183], v[48:63]
	v_mfma_f32_32x32x16_bf16 v[32:47], v[176:179], v[188:191], v[32:47]
	s_waitcnt lgkmcnt(0)
	v_mfma_f32_32x32x16_bf16 v[16:31], v[192:195], v[180:183], v[16:31]
	ds_read_b128 v[168:171], v129 offset:18496
	ds_read_b128 v[172:175], v128 offset:64
	ds_read_b128 v[176:179], v128 offset:96
	ds_read_b128 v[180:183], v128 offset:4672
	ds_read_b128 v[184:187], v128 offset:4704
	v_mfma_f32_32x32x16_bf16 v[0:15], v[192:195], v[188:191], v[0:15]
	ds_read_b128 v[188:191], v129 offset:18528
	ds_read_b128 v[192:195], v129 offset:23104
	ds_read_b128 v[196:199], v129 offset:23136
	s_setprio 0
	s_waitcnt vmcnt(15)
	ds_write_b128 v130, v[96:99] offset:36864
	s_waitcnt vmcnt(14)
	ds_write_b128 v130, v[100:103] offset:41472
	s_waitcnt vmcnt(13)
	ds_write_b128 v130, v[104:107] offset:46080
	s_waitcnt vmcnt(12)
	ds_write_b128 v130, v[108:111] offset:50688
	v_lshl_add_u64 v[96:97], v[150:151], 0, v[156:157]
	v_add_co_u32_e32 v152, vcc, s83, v96
	v_lshl_add_u64 v[98:99], v[148:149], 0, v[156:157]
	s_nop 0
	v_addc_co_u32_e32 v153, vcc, 0, v97, vcc
	v_add_co_u32_e32 v200, vcc, s84, v96
	s_waitcnt lgkmcnt(10)
	v_mfma_f32_32x32x16_bf16 v[48:63], v[172:175], v[168:171], v[48:63]
	v_addc_co_u32_e32 v201, vcc, 0, v97, vcc
	v_add_co_u32_e32 v202, vcc, s85, v96
	s_waitcnt vmcnt(11)
	ds_write_b128 v130, v[112:115] offset:55296
	s_waitcnt vmcnt(10)
	ds_write_b128 v130, v[116:119] offset:59904
	s_waitcnt vmcnt(9)
	ds_write_b128 v130, v[120:123] offset:64512
	s_waitcnt vmcnt(8)
	ds_write_b128 v131, v[124:127] offset:13824
	v_addc_co_u32_e32 v203, vcc, 0, v97, vcc
	s_waitcnt lgkmcnt(9)
	v_mfma_f32_32x32x16_bf16 v[32:47], v[172:175], v[192:195], v[32:47]
	v_add_co_u32_e32 v204, vcc, s86, v96
	v_lshl_add_u64 v[148:149], v[148:149], 0, s[94:95]
	s_nop 0
	v_addc_co_u32_e32 v205, vcc, 0, v97, vcc
	v_add_co_u32_e32 v206, vcc, s45, v98
	v_mfma_f32_32x32x16_bf16 v[16:31], v[180:183], v[168:171], v[16:31]
	s_nop 0
	v_addc_co_u32_e32 v207, vcc, 0, v99, vcc
	v_add_co_u32_e32 v208, vcc, s46, v98
	v_lshl_add_u64 v[150:151], v[150:151], 0, s[94:95]
	s_nop 0
	v_addc_co_u32_e32 v209, vcc, 0, v99, vcc
	v_mfma_f32_32x32x16_bf16 v[0:15], v[180:183], v[192:195], v[0:15]
	v_add_co_u32_e32 v210, vcc, s47, v98
	s_nop 1
	v_addc_co_u32_e32 v211, vcc, 0, v99, vcc
	v_add_co_u32_e32 v212, vcc, s48, v98
	v_mfma_f32_32x32x16_bf16 v[48:63], v[176:179], v[188:191], v[48:63]
	s_nop 0
	v_addc_co_u32_e32 v213, vcc, 0, v99, vcc
	global_load_dwordx4 v[96:99], v[152:153], off offset:2176
	global_load_dwordx4 v[100:103], v[200:201], off offset:2176
	global_load_dwordx4 v[104:107], v[202:203], off offset:2176
	global_load_dwordx4 v[108:111], v[204:205], off offset:2176
	global_load_dwordx4 v[112:115], v[206:207], off offset:2176
	global_load_dwordx4 v[116:119], v[208:209], off offset:2176
	global_load_dwordx4 v[120:123], v[210:211], off offset:2176
	global_load_dwordx4 v[124:127], v[212:213], off offset:2176
	s_waitcnt lgkmcnt(0)
	s_barrier
	s_setprio 1
	v_mfma_f32_32x32x16_bf16 v[32:47], v[176:179], v[196:199], v[32:47]
	ds_read_b128 v[168:171], v128 offset:36864
	ds_read_b128 v[172:175], v129 offset:55296
	ds_read_b128 v[176:179], v128 offset:36896
	ds_read_b128 v[180:183], v129 offset:55328
	v_mfma_f32_32x32x16_bf16 v[16:31], v[184:187], v[188:191], v[16:31]
	v_mfma_f32_32x32x16_bf16 v[0:15], v[184:187], v[196:199], v[0:15]
	ds_read_b128 v[184:187], v129 offset:59904
	ds_read_b128 v[188:191], v129 offset:59936
	s_waitcnt lgkmcnt(4)
	v_mfma_f32_32x32x16_bf16 v[48:63], v[168:171], v[172:175], v[48:63]
	s_waitcnt lgkmcnt(1)
	v_mfma_f32_32x32x16_bf16 v[32:47], v[168:171], v[184:187], v[32:47]
	ds_read_b128 v[168:171], v128 offset:41472
	ds_read_b128 v[192:195], v128 offset:41504
	s_waitcnt lgkmcnt(1)
	v_mfma_f32_32x32x16_bf16 v[16:31], v[168:171], v[172:175], v[16:31]
	v_mfma_f32_32x32x16_bf16 v[0:15], v[168:171], v[184:187], v[0:15]
	v_mfma_f32_32x32x16_bf16 v[48:63], v[176:179], v[180:183], v[48:63]
	v_mfma_f32_32x32x16_bf16 v[32:47], v[176:179], v[188:191], v[32:47]
	s_waitcnt lgkmcnt(0)
	v_mfma_f32_32x32x16_bf16 v[16:31], v[192:195], v[180:183], v[16:31]
	ds_read_b128 v[168:171], v128 offset:36928
	ds_read_b128 v[172:175], v129 offset:55360
	ds_read_b128 v[176:179], v128 offset:36960
	ds_read_b128 v[180:183], v129 offset:55392
	v_mfma_f32_32x32x16_bf16 v[0:15], v[192:195], v[188:191], v[0:15]
	ds_read_b128 v[184:187], v129 offset:59968
	ds_read_b128 v[188:191], v129 offset:60000
	s_waitcnt lgkmcnt(4)
	v_mfma_f32_32x32x16_bf16 v[48:63], v[168:171], v[172:175], v[48:63]
	s_waitcnt lgkmcnt(1)
	v_mfma_f32_32x32x16_bf16 v[32:47], v[168:171], v[184:187], v[32:47]
	ds_read_b128 v[168:171], v128 offset:41536
	ds_read_b128 v[192:195], v128 offset:41568
	s_setprio 0
	s_waitcnt vmcnt(13)
	ds_write_b128 v130, v[92:95]
	ds_write_b128 v130, v[64:67] offset:4608
	ds_write_b128 v130, v[68:71] offset:9216
	s_waitcnt vmcnt(11)
	ds_write_b128 v130, v[84:87] offset:13824
	ds_write_b128 v130, v[72:75] offset:18432
	s_waitcnt vmcnt(10)
	ds_write_b128 v130, v[76:79] offset:23040
	s_waitcnt vmcnt(9)
	ds_write_b128 v130, v[80:83] offset:27648
	s_waitcnt vmcnt(8)
	ds_write_b128 v130, v[88:91] offset:32256
	global_load_dwordx4 v[92:95], v[152:153], off offset:2304
	global_load_dwordx4 v[64:67], v[200:201], off offset:2304
	global_load_dwordx4 v[68:71], v[202:203], off offset:2304
	global_load_dwordx4 v[84:87], v[204:205], off offset:2304
	global_load_dwordx4 v[72:75], v[206:207], off offset:2304
	global_load_dwordx4 v[76:79], v[208:209], off offset:2304
	global_load_dwordx4 v[80:83], v[210:211], off offset:2304
	global_load_dwordx4 v[88:91], v[212:213], off offset:2304
	s_waitcnt lgkmcnt(0)
	s_barrier
; DI void gemm_128_deep(const bf16_t* __restrict__ A, int lda, const bf16_t* __restrict__ B, int ldb, int K, f32x16 (&acc)[2][2], bf16_t* sA, bf16_t* sBunused) {
;     ...
;   for (int k0 = 0; k0 < K - 256; k0 += 128) {
;     MMA_TILE(0)
;     ST_LDS(1, qa0, qa1, qa2, qa3, qb0, qb1, qb2, qb3)
;     GL_Q(k0 + 192)
;     __syncthreads();
;     MMA_TILE(1)
;     ST_LDS(0, pa0, pa1, pa2, pa3, pb0, pb1, pb2, pb3)
;     GL_P(k0 + 256)
;     __syncthreads();
;   }
;   MMA_TILE(0)
;   ST_LDS(1, qa0, qa1, qa2, qa3, qb0, qb1, qb2, qb3)
;   GL_Q(K - 64)
;   __syncthreads();
;   MMA_TILE(1)
;   ST_LDS(0, pa0, pa1, pa2, pa3, pb0, pb1, pb2, pb3)
;   __syncthreads();
;   MMA_TILE(0)
;   ST_LDS(1, qa0, qa1, qa2, qa3, qb0, qb1, qb2, qb3)
;   __syncthreads();
;   MMA_TILE(1)
;   __syncthreads();
	s_setprio 1
	v_mfma_f32_32x32x16_bf16 v[16:31], v[168:171], v[172:175], v[16:31]
	v_mfma_f32_32x32x16_bf16 v[0:15], v[168:171], v[184:187], v[0:15]
	v_mfma_f32_32x32x16_bf16 v[48:63], v[176:179], v[180:183], v[48:63]
	v_mfma_f32_32x32x16_bf16 v[32:47], v[176:179], v[188:191], v[32:47]
	v_mfma_f32_32x32x16_bf16 v[16:31], v[192:195], v[180:183], v[16:31]
	v_mfma_f32_32x32x16_bf16 v[0:15], v[192:195], v[188:191], v[0:15]
	s_cbranch_scc1 .LBB0_208
	ds_read_b128 v[148:151], v128
	ds_read_b128 v[168:171], v129 offset:18432
	ds_read_b128 v[172:175], v129 offset:23040
	s_mov_b64 s[52:53], -1
	s_cmp_gt_i32 s60, 15
	s_waitcnt lgkmcnt(1)
	v_mfma_f32_32x32x16_bf16 v[48:63], v[148:151], v[168:171], v[48:63]
	s_waitcnt lgkmcnt(0)
	v_mfma_f32_32x32x16_bf16 v[32:47], v[148:151], v[172:175], v[32:47]
	ds_read_b128 v[148:151], v128 offset:4608
	s_waitcnt lgkmcnt(0)
	v_mfma_f32_32x32x16_bf16 v[16:31], v[148:151], v[168:171], v[16:31]
	v_mfma_f32_32x32x16_bf16 v[0:15], v[148:151], v[172:175], v[0:15]
	ds_read_b128 v[148:151], v128 offset:32
	ds_read_b128 v[168:171], v129 offset:18464
	ds_read_b128 v[172:175], v129 offset:23072
	s_waitcnt lgkmcnt(1)
	v_mfma_f32_32x32x16_bf16 v[48:63], v[148:151], v[168:171], v[48:63]
	s_waitcnt lgkmcnt(0)
	v_mfma_f32_32x32x16_bf16 v[32:47], v[148:151], v[172:175], v[32:47]
	ds_read_b128 v[148:151], v128 offset:4640
	s_waitcnt lgkmcnt(0)
	v_mfma_f32_32x32x16_bf16 v[16:31], v[148:151], v[168:171], v[16:31]
	v_mfma_f32_32x32x16_bf16 v[0:15], v[148:151], v[172:175], v[0:15]
	ds_read_b128 v[148:151], v128 offset:64
	ds_read_b128 v[168:171], v129 offset:18496
	ds_read_b128 v[172:175], v129 offset:23104
	s_waitcnt lgkmcnt(1)
	v_mfma_f32_32x32x16_bf16 v[48:63], v[148:151], v[168:171], v[48:63]
	s_waitcnt lgkmcnt(0)
	v_mfma_f32_32x32x16_bf16 v[32:47], v[148:151], v[172:175], v[32:47]
	ds_read_b128 v[148:151], v128 offset:4672
	s_waitcnt lgkmcnt(0)
	v_mfma_f32_32x32x16_bf16 v[16:31], v[148:151], v[168:171], v[16:31]
	v_mfma_f32_32x32x16_bf16 v[0:15], v[148:151], v[172:175], v[0:15]
	ds_read_b128 v[148:151], v128 offset:96
	ds_read_b128 v[168:171], v129 offset:18528
	ds_read_b128 v[172:175], v129 offset:23136
	s_waitcnt lgkmcnt(1)
	v_mfma_f32_32x32x16_bf16 v[48:63], v[148:151], v[168:171], v[48:63]
	s_waitcnt lgkmcnt(0)
	v_mfma_f32_32x32x16_bf16 v[32:47], v[148:151], v[172:175], v[32:47]
	ds_read_b128 v[148:151], v128 offset:4704
	s_setprio 0
	s_waitcnt vmcnt(15)
	ds_write_b128 v130, v[96:99] offset:36864
	s_waitcnt vmcnt(14)
	ds_write_b128 v130, v[100:103] offset:41472
	s_waitcnt vmcnt(13)
	ds_write_b128 v130, v[104:107] offset:46080
	s_waitcnt vmcnt(12)
	ds_write_b128 v130, v[108:111] offset:50688
	s_waitcnt vmcnt(11)
	ds_write_b128 v130, v[112:115] offset:55296
	s_waitcnt vmcnt(10)
	ds_write_b128 v130, v[116:119] offset:59904
	s_waitcnt vmcnt(9)
	ds_write_b128 v130, v[120:123] offset:64512
	s_waitcnt vmcnt(8)
	ds_write_b128 v131, v[124:127] offset:13824
	global_load_dwordx4 v[96:99], v[142:143], off offset:3968
	global_load_dwordx4 v[100:103], v[138:139], off offset:3968
	global_load_dwordx4 v[104:107], v[144:145], off offset:3968
	global_load_dwordx4 v[108:111], v[146:147], off offset:3968
	global_load_dwordx4 v[112:115], v[132:133], off offset:3968
	global_load_dwordx4 v[116:119], v[134:135], off offset:3968
	global_load_dwordx4 v[120:123], v[136:137], off offset:3968
	global_load_dwordx4 v[124:127], v[140:141], off offset:3968
	s_waitcnt lgkmcnt(0)
	s_barrier
	s_setprio 1
	ds_read_b128 v[132:135], v128 offset:36864
	ds_read_b128 v[136:139], v129 offset:55296
	ds_read_b128 v[140:143], v129 offset:59904
	s_waitcnt lgkmcnt(1)
	v_mfma_f32_32x32x16_bf16 v[48:63], v[132:135], v[136:139], v[48:63]
	s_waitcnt lgkmcnt(0)
	v_mfma_f32_32x32x16_bf16 v[32:47], v[132:135], v[140:143], v[32:47]
	ds_read_b128 v[132:135], v128 offset:41472
	v_mfma_f32_32x32x16_bf16 v[16:31], v[148:151], v[168:171], v[16:31]
	v_mfma_f32_32x32x16_bf16 v[0:15], v[148:151], v[172:175], v[0:15]
	s_waitcnt lgkmcnt(0)
	v_mfma_f32_32x32x16_bf16 v[16:31], v[132:135], v[136:139], v[16:31]
	v_mfma_f32_32x32x16_bf16 v[0:15], v[132:135], v[140:143], v[0:15]
	ds_read_b128 v[132:135], v128 offset:36896
	ds_read_b128 v[136:139], v129 offset:55328
	ds_read_b128 v[140:143], v129 offset:59936
	s_waitcnt lgkmcnt(1)
	v_mfma_f32_32x32x16_bf16 v[48:63], v[132:135], v[136:139], v[48:63]
	s_waitcnt lgkmcnt(0)
	v_mfma_f32_32x32x16_bf16 v[32:47], v[132:135], v[140:143], v[32:47]
	ds_read_b128 v[132:135], v128 offset:41504
	s_waitcnt lgkmcnt(0)
	v_mfma_f32_32x32x16_bf16 v[16:31], v[132:135], v[136:139], v[16:31]
	v_mfma_f32_32x32x16_bf16 v[0:15], v[132:135], v[140:143], v[0:15]
	ds_read_b128 v[132:135], v128 offset:36928
	ds_read_b128 v[136:139], v129 offset:55360
	ds_read_b128 v[140:143], v129 offset:59968
	s_waitcnt lgkmcnt(1)
	v_mfma_f32_32x32x16_bf16 v[48:63], v[132:135], v[136:139], v[48:63]
	s_waitcnt lgkmcnt(0)
	v_mfma_f32_32x32x16_bf16 v[32:47], v[132:135], v[140:143], v[32:47]
	ds_read_b128 v[132:135], v128 offset:41536
	s_waitcnt lgkmcnt(0)
	v_mfma_f32_32x32x16_bf16 v[16:31], v[132:135], v[136:139], v[16:31]
	v_mfma_f32_32x32x16_bf16 v[0:15], v[132:135], v[140:143], v[0:15]
	ds_read_b128 v[132:135], v128 offset:36960
	ds_read_b128 v[136:139], v129 offset:55392
	ds_read_b128 v[140:143], v129 offset:60000
	s_waitcnt lgkmcnt(1)
	v_mfma_f32_32x32x16_bf16 v[48:63], v[132:135], v[136:139], v[48:63]
	s_waitcnt lgkmcnt(0)
	v_mfma_f32_32x32x16_bf16 v[32:47], v[132:135], v[140:143], v[32:47]
	ds_read_b128 v[132:135], v128 offset:41568
	s_setprio 0
	s_waitcnt vmcnt(15)
	ds_write_b128 v130, v[92:95]
	s_waitcnt vmcnt(14)
	ds_write_b128 v130, v[64:67] offset:4608
	s_waitcnt vmcnt(13)
	ds_write_b128 v130, v[68:71] offset:9216
	s_waitcnt vmcnt(12)
	ds_write_b128 v130, v[84:87] offset:13824
	s_waitcnt vmcnt(11)
	ds_write_b128 v130, v[72:75] offset:18432
	s_waitcnt vmcnt(10)
	ds_write_b128 v130, v[76:79] offset:23040
	s_waitcnt vmcnt(9)
	ds_write_b128 v130, v[80:83] offset:27648
	s_waitcnt vmcnt(8)
	ds_write_b128 v130, v[88:91] offset:32256
	s_waitcnt lgkmcnt(0)
	s_barrier
; DI void gemm_128_deep(const bf16_t* __restrict__ A, int lda, const bf16_t* __restrict__ B, int ldb, int K, f32x16 (&acc)[2][2], bf16_t* sA, bf16_t* sBunused) {
;     ...
;   MMA_TILE(0)
;   ST_LDS(1, qa0, qa1, qa2, qa3, qb0, qb1, qb2, qb3)
;   GL_Q(K - 64)
;   __syncthreads();
;   MMA_TILE(1)
;   ST_LDS(0, pa0, pa1, pa2, pa3, pb0, pb1, pb2, pb3)
;   __syncthreads();
;   MMA_TILE(0)
;   ST_LDS(1, qa0, qa1, qa2, qa3, qb0, qb1, qb2, qb3)
;   __syncthreads();
;   MMA_TILE(1)
;   __syncthreads();
	s_setprio 1
	ds_read_b128 v[64:67], v128
	ds_read_b128 v[68:71], v129 offset:18432
	ds_read_b128 v[72:75], v129 offset:23040
	s_waitcnt lgkmcnt(1)
	v_mfma_f32_32x32x16_bf16 v[48:63], v[64:67], v[68:71], v[48:63]
	s_waitcnt lgkmcnt(0)
	v_mfma_f32_32x32x16_bf16 v[32:47], v[64:67], v[72:75], v[32:47]
	ds_read_b128 v[64:67], v128 offset:4608
	v_mfma_f32_32x32x16_bf16 v[16:31], v[132:135], v[136:139], v[16:31]
	v_mfma_f32_32x32x16_bf16 v[0:15], v[132:135], v[140:143], v[0:15]
	s_waitcnt lgkmcnt(0)
	v_mfma_f32_32x32x16_bf16 v[16:31], v[64:67], v[68:71], v[16:31]
	v_mfma_f32_32x32x16_bf16 v[0:15], v[64:67], v[72:75], v[0:15]
	ds_read_b128 v[64:67], v128 offset:32
	ds_read_b128 v[68:71], v129 offset:18464
	ds_read_b128 v[72:75], v129 offset:23072
	s_waitcnt lgkmcnt(1)
	v_mfma_f32_32x32x16_bf16 v[48:63], v[64:67], v[68:71], v[48:63]
	s_waitcnt lgkmcnt(0)
	v_mfma_f32_32x32x16_bf16 v[32:47], v[64:67], v[72:75], v[32:47]
	ds_read_b128 v[64:67], v128 offset:4640
	s_waitcnt lgkmcnt(0)
	v_mfma_f32_32x32x16_bf16 v[16:31], v[64:67], v[68:71], v[16:31]
	v_mfma_f32_32x32x16_bf16 v[0:15], v[64:67], v[72:75], v[0:15]
	ds_read_b128 v[64:67], v128 offset:64
	ds_read_b128 v[68:71], v129 offset:18496
	ds_read_b128 v[72:75], v129 offset:23104
	s_waitcnt lgkmcnt(1)
	v_mfma_f32_32x32x16_bf16 v[48:63], v[64:67], v[68:71], v[48:63]
	s_waitcnt lgkmcnt(0)
	v_mfma_f32_32x32x16_bf16 v[32:47], v[64:67], v[72:75], v[32:47]
	ds_read_b128 v[64:67], v128 offset:4672
	s_waitcnt lgkmcnt(0)
	v_mfma_f32_32x32x16_bf16 v[16:31], v[64:67], v[68:71], v[16:31]
	v_mfma_f32_32x32x16_bf16 v[0:15], v[64:67], v[72:75], v[0:15]
	ds_read_b128 v[64:67], v128 offset:96
	ds_read_b128 v[68:71], v129 offset:18528
	ds_read_b128 v[72:75], v129 offset:23136
	s_waitcnt lgkmcnt(1)
	v_mfma_f32_32x32x16_bf16 v[48:63], v[64:67], v[68:71], v[48:63]
	s_waitcnt lgkmcnt(0)
	v_mfma_f32_32x32x16_bf16 v[32:47], v[64:67], v[72:75], v[32:47]
	ds_read_b128 v[64:67], v128 offset:4704
	s_setprio 0
	s_waitcnt vmcnt(7)
	ds_write_b128 v130, v[96:99] offset:36864
	s_waitcnt vmcnt(6)
	ds_write_b128 v130, v[100:103] offset:41472
	s_waitcnt vmcnt(5)
	ds_write_b128 v130, v[104:107] offset:46080
	s_waitcnt vmcnt(4)
	ds_write_b128 v130, v[108:111] offset:50688
	s_waitcnt vmcnt(3)
	ds_write_b128 v130, v[112:115] offset:55296
	s_waitcnt vmcnt(2)
	ds_write_b128 v130, v[116:119] offset:59904
	s_waitcnt vmcnt(1)
	ds_write_b128 v130, v[120:123] offset:64512
	s_waitcnt vmcnt(0)
	ds_write_b128 v131, v[124:127] offset:13824
	s_waitcnt lgkmcnt(0)
	s_barrier
	s_setprio 1
	v_mfma_f32_32x32x16_bf16 v[16:31], v[64:67], v[68:71], v[16:31]
	v_mfma_f32_32x32x16_bf16 v[0:15], v[64:67], v[72:75], v[0:15]
	ds_read_b128 v[64:67], v128 offset:36864
	ds_read_b128 v[68:71], v129 offset:55296
	ds_read_b128 v[72:75], v129 offset:59904
	s_waitcnt lgkmcnt(1)
	v_mfma_f32_32x32x16_bf16 v[48:63], v[64:67], v[68:71], v[48:63]
	s_waitcnt lgkmcnt(0)
	v_mfma_f32_32x32x16_bf16 v[32:47], v[64:67], v[72:75], v[32:47]
	ds_read_b128 v[64:67], v128 offset:41472
	s_waitcnt lgkmcnt(0)
	v_mfma_f32_32x32x16_bf16 v[16:31], v[64:67], v[68:71], v[16:31]
	v_mfma_f32_32x32x16_bf16 v[0:15], v[64:67], v[72:75], v[0:15]
	ds_read_b128 v[64:67], v128 offset:36896
	ds_read_b128 v[68:71], v129 offset:55328
	ds_read_b128 v[72:75], v129 offset:59936
	s_waitcnt lgkmcnt(1)
	v_mfma_f32_32x32x16_bf16 v[48:63], v[64:67], v[68:71], v[48:63]
	s_waitcnt lgkmcnt(0)
	v_mfma_f32_32x32x16_bf16 v[32:47], v[64:67], v[72:75], v[32:47]
	ds_read_b128 v[64:67], v128 offset:41504
	s_waitcnt lgkmcnt(0)
	v_mfma_f32_32x32x16_bf16 v[16:31], v[64:67], v[68:71], v[16:31]
	v_mfma_f32_32x32x16_bf16 v[0:15], v[64:67], v[72:75], v[0:15]
	ds_read_b128 v[64:67], v128 offset:36928
	ds_read_b128 v[68:71], v129 offset:55360
	ds_read_b128 v[72:75], v129 offset:59968
	s_waitcnt lgkmcnt(1)
	v_mfma_f32_32x32x16_bf16 v[48:63], v[64:67], v[68:71], v[48:63]
	s_waitcnt lgkmcnt(0)
	v_mfma_f32_32x32x16_bf16 v[32:47], v[64:67], v[72:75], v[32:47]
	ds_read_b128 v[64:67], v128 offset:41536
	s_waitcnt lgkmcnt(0)
	v_mfma_f32_32x32x16_bf16 v[16:31], v[64:67], v[68:71], v[16:31]
	v_mfma_f32_32x32x16_bf16 v[0:15], v[64:67], v[72:75], v[0:15]
	ds_read_b128 v[64:67], v128 offset:36960
	ds_read_b128 v[68:71], v129 offset:55392
	ds_read_b128 v[72:75], v129 offset:60000
	s_waitcnt lgkmcnt(1)
	v_mfma_f32_32x32x16_bf16 v[48:63], v[64:67], v[68:71], v[48:63]
	s_waitcnt lgkmcnt(0)
	v_mfma_f32_32x32x16_bf16 v[32:47], v[64:67], v[72:75], v[32:47]
	ds_read_b128 v[64:67], v128 offset:41568
	s_waitcnt lgkmcnt(0)
	s_barrier
	s_setprio 1
	v_mfma_f32_32x32x16_bf16 v[16:31], v[64:67], v[68:71], v[16:31]
	v_mfma_f32_32x32x16_bf16 v[0:15], v[64:67], v[72:75], v[0:15]
	s_setprio 2
	s_cbranch_scc1 .LBB0_213
	s_andn2_b64 vcc, exec, s[52:53]
	s_cbranch_vccz .LBB0_225

; DI void xcd_barrier(const XcdBarrier& b) {
;   asm volatile("s_waitcnt vmcnt(0)" ::: "memory");
;   __syncthreads();
;   if (threadIdx.x == 0) {
;     unsigned* bar = b.bar;
;     __builtin_amdgcn_s_waitcnt(0);
;     unsigned nloc = b.st[0], nx = b.st[1];
;     if (nloc == 0u) { xcd_barrier_complete(bar, b.x, nloc, nx); b.st[0] = nloc; b.st[1] = nx; }
.LBB0_249:
	s_setprio 0
	s_waitcnt vmcnt(0)
	s_waitcnt lgkmcnt(0)
	s_barrier
	s_mov_b64 s[2:3], exec
	v_readlane_b32 s4, v253, 2
	v_readlane_b32 s5, v253, 3
	s_and_b64 s[4:5], s[2:3], s[4:5]
	s_mov_b64 exec, s[4:5]
	s_cbranch_execz .LBB0_302
	s_waitcnt vmcnt(0) expcnt(0) lgkmcnt(0)
	ds_read_b32 v2, v217
	ds_read_b32 v0, v218
	s_waitcnt lgkmcnt(1)
	v_cmp_ne_u32_e32 vcc, 0, v2
	s_cbranch_vccnz .LBB0_266
	v_readlane_b32 s6, v253, 6
	v_readlane_b32 s7, v253, 7
	s_load_dwordx2 s[4:5], s[6:7], 0x0
	s_nop 0
	s_load_dword s6, s[6:7], 0x8
	s_mov_b32 s13, 1
	s_waitcnt lgkmcnt(0)
	s_mul_i32 s12, s5, s4
	s_mul_i32 s12, s12, s6
	s_branch .LBB0_253

; DI void gemm_128_2set(const bf16_t* __restrict__ A, int lda, const bf16_t* __restrict__ B, int ldb, int K, f32x16 (&acc)[2][2], bf16_t* sA, bf16_t* sB) {
;     ...
;   GL2_P(0)
;   GL2_Q(64)
;   for (int k0 = 0; k0 < K - 128; k0 += 128) {
;     __syncthreads();
;     ST2(pa0, pa1, pa2, pa3, pb0, pb1, pb2, pb3)
;     __syncthreads();
;     GL2_P(k0 + 128)
;     MMA2()
;     __syncthreads();
;     ST2(qa0, qa1, qa2, qa3, qb0, qb1, qb2, qb3)
;     __syncthreads();
;     GL2_Q(k0 + 192)
;     MMA2()
;   }
.LBB0_883:
	s_waitcnt lgkmcnt(0)
	s_barrier
	s_setprio 1
	s_setprio 0
	s_waitcnt vmcnt(15)
	ds_write_b128 v134, v[96:99]
	s_waitcnt vmcnt(14)
	ds_write_b128 v134, v[100:103] offset:4608
	s_waitcnt vmcnt(13)
	ds_write_b128 v134, v[104:107] offset:9216
	s_waitcnt vmcnt(12)
	ds_write_b128 v134, v[108:111] offset:13824
	s_waitcnt vmcnt(11)
	ds_write_b128 v134, v[112:115] offset:18432
	s_waitcnt vmcnt(10)
	ds_write_b128 v134, v[116:119] offset:23040
	s_waitcnt vmcnt(9)
	ds_write_b128 v134, v[120:123] offset:27648
	s_waitcnt vmcnt(8)
	ds_write_b128 v134, v[124:127] offset:32256
	s_waitcnt lgkmcnt(0)
	s_barrier
	s_setprio 1
	ds_read_b128 v[96:99], v128
	ds_read_b128 v[100:103], v129 offset:18432
	ds_read_b128 v[104:107], v128 offset:32
	ds_read_b128 v[108:111], v129 offset:18464
	ds_read_b128 v[112:115], v129 offset:23040
	ds_read_b128 v[116:119], v129 offset:23072
	s_waitcnt lgkmcnt(4)
	v_mfma_f32_32x32x16_bf16 v[48:63], v[96:99], v[100:103], v[48:63]
	s_mov_b32 s52, 0x17864000
	s_addk_i32 s51, 0x80
	s_cmpk_lt_u32 s51, 0x700
	s_waitcnt lgkmcnt(1)
	v_mfma_f32_32x32x16_bf16 v[32:47], v[96:99], v[112:115], v[32:47]
	ds_read_b128 v[96:99], v128 offset:4608
	ds_read_b128 v[120:123], v128 offset:4640
	s_waitcnt lgkmcnt(1)
	v_mfma_f32_32x32x16_bf16 v[16:31], v[96:99], v[100:103], v[16:31]
	v_mfma_f32_32x32x16_bf16 v[0:15], v[96:99], v[112:115], v[0:15]
	v_lshl_add_u64 v[112:113], v[132:133], 0, v[156:157]
	ds_read_b128 v[96:99], v128 offset:4672
	ds_read_b128 v[100:103], v128 offset:64
	ds_read_b128 v[136:139], v128 offset:96
	v_add_co_u32_e32 v196, vcc, s83, v112
	v_lshl_add_u64 v[114:115], v[130:131], 0, v[156:157]
	s_nop 0
	v_addc_co_u32_e32 v197, vcc, 0, v113, vcc
	v_mfma_f32_32x32x16_bf16 v[48:63], v[104:107], v[108:111], v[48:63]
	v_add_co_u32_e32 v198, vcc, s84, v112
	v_lshl_add_u64 v[130:131], v[130:131], 0, s[94:95]
	s_nop 0
	v_addc_co_u32_e32 v199, vcc, 0, v113, vcc
	v_add_co_u32_e32 v200, vcc, s85, v112
	v_mfma_f32_32x32x16_bf16 v[32:47], v[104:107], v[116:119], v[32:47]
	s_nop 0
	v_addc_co_u32_e32 v201, vcc, 0, v113, vcc
	v_add_co_u32_e32 v202, vcc, s86, v112
	v_lshl_add_u64 v[132:133], v[132:133], 0, s[94:95]
	s_nop 0
	v_addc_co_u32_e32 v203, vcc, 0, v113, vcc
	s_waitcnt lgkmcnt(3)
	v_mfma_f32_32x32x16_bf16 v[16:31], v[120:123], v[108:111], v[16:31]
	ds_read_b128 v[184:187], v128 offset:4704
	ds_read_b128 v[104:107], v129 offset:18496
	ds_read_b128 v[188:191], v129 offset:18528
	ds_read_b128 v[108:111], v129 offset:23104
	ds_read_b128 v[192:195], v129 offset:23136
	v_add_co_u32_e32 v204, vcc, s52, v114
	s_mov_b32 s52, 0x17884000
	s_nop 0
	v_addc_co_u32_e32 v205, vcc, 0, v115, vcc
	v_add_co_u32_e32 v206, vcc, s52, v114
	v_mfma_f32_32x32x16_bf16 v[0:15], v[120:123], v[116:119], v[0:15]
	s_nop 0
	v_addc_co_u32_e32 v207, vcc, 0, v115, vcc
	s_mov_b32 s52, 0x178a4000
	v_add_co_u32_e32 v208, vcc, s52, v114
	s_mov_b32 s52, 0x178c4000
	s_nop 0
	v_addc_co_u32_e32 v209, vcc, 0, v115, vcc
	s_waitcnt lgkmcnt(3)
	v_mfma_f32_32x32x16_bf16 v[48:63], v[100:103], v[104:107], v[48:63]
	v_add_co_u32_e32 v210, vcc, s52, v114
	s_nop 1
	v_addc_co_u32_e32 v211, vcc, 0, v115, vcc
	s_waitcnt lgkmcnt(1)
	v_mfma_f32_32x32x16_bf16 v[32:47], v[100:103], v[108:111], v[32:47]
	v_mfma_f32_32x32x16_bf16 v[16:31], v[96:99], v[104:107], v[16:31]
	v_mfma_f32_32x32x16_bf16 v[0:15], v[96:99], v[108:111], v[0:15]
	global_load_dwordx4 v[96:99], v[196:197], off offset:2048
	global_load_dwordx4 v[100:103], v[198:199], off offset:2048
	global_load_dwordx4 v[104:107], v[200:201], off offset:2048
	global_load_dwordx4 v[108:111], v[202:203], off offset:2048
	global_load_dwordx4 v[112:115], v[204:205], off offset:2048
	global_load_dwordx4 v[116:119], v[206:207], off offset:2048
	global_load_dwordx4 v[120:123], v[208:209], off offset:2048
	global_load_dwordx4 v[124:127], v[210:211], off offset:2048
	s_waitcnt lgkmcnt(0)
	s_barrier
	s_setprio 1
	s_setprio 0
	s_waitcnt vmcnt(15)
	ds_write_b128 v134, v[80:83]
	s_waitcnt vmcnt(14)
	ds_write_b128 v134, v[64:67] offset:4608
	s_waitcnt vmcnt(13)
	ds_write_b128 v134, v[68:71] offset:9216
	s_waitcnt vmcnt(12)
	ds_write_b128 v134, v[72:75] offset:13824
	s_waitcnt vmcnt(11)
	ds_write_b128 v134, v[76:79] offset:18432
	s_waitcnt vmcnt(10)
	ds_write_b128 v134, v[84:87] offset:23040
	s_waitcnt vmcnt(9)
	ds_write_b128 v134, v[88:91] offset:27648
	s_waitcnt vmcnt(8)
	ds_write_b128 v134, v[92:95] offset:32256
	v_mfma_f32_32x32x16_bf16 v[48:63], v[136:139], v[188:191], v[48:63]
	s_waitcnt lgkmcnt(0)
	s_barrier
; DI void gemm_128_2set(const bf16_t* __restrict__ A, int lda, const bf16_t* __restrict__ B, int ldb, int K, f32x16 (&acc)[2][2], bf16_t* sA, bf16_t* sB) {
;     ...
;   for (int k0 = 0; k0 < K - 128; k0 += 128) {
;     __syncthreads();
;     ST2(pa0, pa1, pa2, pa3, pb0, pb1, pb2, pb3)
;     __syncthreads();
;     GL2_P(k0 + 128)
;     MMA2()
;     __syncthreads();
;     ST2(qa0, qa1, qa2, qa3, qb0, qb1, qb2, qb3)
;     __syncthreads();
;     GL2_Q(k0 + 192)
;     MMA2()
;   }
;   __syncthreads();
;   ST2(pa0, pa1, pa2, pa3, pb0, pb1, pb2, pb3)
;   __syncthreads();
;   MMA2()
;   __syncthreads();
;   ST2(qa0, qa1, qa2, qa3, qb0, qb1, qb2, qb3)
;   __syncthreads();
;   MMA2()
	s_setprio 1
	ds_read_b128 v[64:67], v128
	ds_read_b128 v[68:71], v129 offset:18432
	ds_read_b128 v[72:75], v128 offset:32
	ds_read_b128 v[76:79], v129 offset:18464
	ds_read_b128 v[80:83], v129 offset:23040
	ds_read_b128 v[84:87], v129 offset:23072
	v_mfma_f32_32x32x16_bf16 v[32:47], v[136:139], v[192:195], v[32:47]
	v_mfma_f32_32x32x16_bf16 v[16:31], v[184:187], v[188:191], v[16:31]
	v_mfma_f32_32x32x16_bf16 v[0:15], v[184:187], v[192:195], v[0:15]
	s_waitcnt lgkmcnt(4)
	v_mfma_f32_32x32x16_bf16 v[48:63], v[64:67], v[68:71], v[48:63]
	s_waitcnt lgkmcnt(1)
	v_mfma_f32_32x32x16_bf16 v[32:47], v[64:67], v[80:83], v[32:47]
	ds_read_b128 v[64:67], v128 offset:4608
	ds_read_b128 v[88:91], v128 offset:4640
	s_waitcnt lgkmcnt(1)
	v_mfma_f32_32x32x16_bf16 v[16:31], v[64:67], v[68:71], v[16:31]
	v_mfma_f32_32x32x16_bf16 v[0:15], v[64:67], v[80:83], v[0:15]
	v_mfma_f32_32x32x16_bf16 v[48:63], v[72:75], v[76:79], v[48:63]
	v_mfma_f32_32x32x16_bf16 v[32:47], v[72:75], v[84:87], v[32:47]
	ds_read_b128 v[64:67], v128 offset:64
	ds_read_b128 v[68:71], v129 offset:18496
	ds_read_b128 v[72:75], v128 offset:96
	ds_read_b128 v[92:95], v129 offset:18528
	s_waitcnt lgkmcnt(4)
	v_mfma_f32_32x32x16_bf16 v[16:31], v[88:91], v[76:79], v[16:31]
	ds_read_b128 v[76:79], v129 offset:23104
	ds_read_b128 v[136:139], v129 offset:23136
	v_mfma_f32_32x32x16_bf16 v[0:15], v[88:91], v[84:87], v[0:15]
	s_waitcnt lgkmcnt(4)
	v_mfma_f32_32x32x16_bf16 v[48:63], v[64:67], v[68:71], v[48:63]
	s_waitcnt lgkmcnt(1)
	v_mfma_f32_32x32x16_bf16 v[32:47], v[64:67], v[76:79], v[32:47]
	ds_read_b128 v[64:67], v128 offset:4672
	ds_read_b128 v[184:187], v128 offset:4704
	s_waitcnt lgkmcnt(1)
	v_mfma_f32_32x32x16_bf16 v[16:31], v[64:67], v[68:71], v[16:31]
	v_mfma_f32_32x32x16_bf16 v[0:15], v[64:67], v[76:79], v[0:15]
	v_mfma_f32_32x32x16_bf16 v[48:63], v[72:75], v[92:95], v[48:63]
	v_mfma_f32_32x32x16_bf16 v[32:47], v[72:75], v[136:139], v[32:47]
	global_load_dwordx4 v[80:83], v[196:197], off offset:2176
	global_load_dwordx4 v[64:67], v[198:199], off offset:2176
	global_load_dwordx4 v[68:71], v[200:201], off offset:2176
	global_load_dwordx4 v[72:75], v[202:203], off offset:2176
	global_load_dwordx4 v[76:79], v[204:205], off offset:2176
	global_load_dwordx4 v[84:87], v[206:207], off offset:2176
	global_load_dwordx4 v[88:91], v[208:209], off offset:2176
	s_waitcnt lgkmcnt(0)
	v_mfma_f32_32x32x16_bf16 v[16:31], v[184:187], v[92:95], v[16:31]
	global_load_dwordx4 v[92:95], v[210:211], off offset:2176
	v_mfma_f32_32x32x16_bf16 v[0:15], v[184:187], v[136:139], v[0:15]
	s_cbranch_scc1 .LBB0_883
	s_barrier
	s_setprio 1
	s_setprio 0
	s_waitcnt vmcnt(15)
	ds_write_b128 v134, v[96:99]
	s_waitcnt vmcnt(14)
	ds_write_b128 v134, v[100:103] offset:4608
	s_waitcnt vmcnt(13)
	ds_write_b128 v134, v[104:107] offset:9216
	s_waitcnt vmcnt(12)
	ds_write_b128 v134, v[108:111] offset:13824
	s_waitcnt vmcnt(11)
	ds_write_b128 v134, v[112:115] offset:18432
	s_waitcnt vmcnt(10)
	ds_write_b128 v134, v[116:119] offset:23040
	s_waitcnt vmcnt(9)
	ds_write_b128 v134, v[120:123] offset:27648
	s_waitcnt vmcnt(8)
	ds_write_b128 v134, v[124:127] offset:32256
	s_waitcnt lgkmcnt(0)
	s_barrier
	s_setprio 1
	ds_read_b128 v[96:99], v128 offset:4608
	ds_read_b128 v[100:103], v129 offset:23040
	ds_read_b128 v[104:107], v128
	ds_read_b128 v[108:111], v128 offset:32
	ds_read_b128 v[112:115], v129 offset:18432
	ds_read_b128 v[116:119], v129 offset:18464
	s_waitcnt lgkmcnt(1)
	v_mfma_f32_32x32x16_bf16 v[48:63], v[104:107], v[112:115], v[48:63]
	s_add_i32 s73, s73, 1
	s_addk_i32 s50, 0x800
	s_cmp_eq_u32 s73, 4
	v_mfma_f32_32x32x16_bf16 v[32:47], v[104:107], v[100:103], v[32:47]
	v_mfma_f32_32x32x16_bf16 v[16:31], v[96:99], v[112:115], v[16:31]
	v_mfma_f32_32x32x16_bf16 v[0:15], v[96:99], v[100:103], v[0:15]
	ds_read_b128 v[96:99], v128 offset:4640
	ds_read_b128 v[100:103], v129 offset:23072
	s_waitcnt lgkmcnt(2)
	v_mfma_f32_32x32x16_bf16 v[48:63], v[108:111], v[116:119], v[48:63]
	s_waitcnt lgkmcnt(0)
	v_mfma_f32_32x32x16_bf16 v[32:47], v[108:111], v[100:103], v[32:47]
	v_mfma_f32_32x32x16_bf16 v[16:31], v[96:99], v[116:119], v[16:31]
	v_mfma_f32_32x32x16_bf16 v[0:15], v[96:99], v[100:103], v[0:15]
	ds_read_b128 v[96:99], v128 offset:64
	ds_read_b128 v[100:103], v128 offset:4672
	ds_read_b128 v[104:107], v129 offset:18496
	ds_read_b128 v[108:111], v129 offset:23104
	s_waitcnt lgkmcnt(1)
	v_mfma_f32_32x32x16_bf16 v[48:63], v[96:99], v[104:107], v[48:63]
	s_waitcnt lgkmcnt(0)
	v_mfma_f32_32x32x16_bf16 v[32:47], v[96:99], v[108:111], v[32:47]
	v_mfma_f32_32x32x16_bf16 v[16:31], v[100:103], v[104:107], v[16:31]
	v_mfma_f32_32x32x16_bf16 v[0:15], v[100:103], v[108:111], v[0:15]
	ds_read_b128 v[96:99], v128 offset:96
	ds_read_b128 v[100:103], v128 offset:4704
	ds_read_b128 v[104:107], v129 offset:18528
	ds_read_b128 v[108:111], v129 offset:23136
	s_waitcnt lgkmcnt(0)
	s_barrier
	s_setprio 1
	s_setprio 0
	s_waitcnt vmcnt(7)
	ds_write_b128 v134, v[80:83]
	s_waitcnt vmcnt(6)
	ds_write_b128 v134, v[64:67] offset:4608
	s_waitcnt vmcnt(5)
	ds_write_b128 v134, v[68:71] offset:9216
	s_waitcnt vmcnt(4)
	ds_write_b128 v134, v[72:75] offset:13824
	s_waitcnt vmcnt(3)
	ds_write_b128 v134, v[76:79] offset:18432
	s_waitcnt vmcnt(2)
	ds_write_b128 v134, v[84:87] offset:23040
	s_waitcnt vmcnt(1)
	ds_write_b128 v134, v[88:91] offset:27648
	s_waitcnt vmcnt(0)
	ds_write_b128 v134, v[92:95] offset:32256
	s_waitcnt lgkmcnt(0)
	s_barrier
; DI float sigmf(float x) { return __builtin_amdgcn_rcpf(1.f + __expf(-x)); }
; DI void phase_merge(CP p, const Ptrs& w, int l, bf16_t* sA, bf16_t* sB, unsigned* sU) {
;     ...
; #pragma unroll
;       for (int a = 0; a < 2; ++a)
; #pragma unroll
;         for (int c = 0; c < 2; ++c)
; #pragma unroll
;           for (int i = 0; i < 8; ++i) {
;             unsigned uv = sU[((a * 2 + c) * 8 + i) * 256 + tid];
;             float u0 = __uint_as_float(uv << 16), u1 = __uint_as_float(uv & 0xffff0000u);
;             const unsigned tv = totp[a][c][i];
;             float t0 = __uint_as_float(tv << 16) + sigmf(G[a][c][2 * i]) * u0;
;             float t1 = __uint_as_float(tv & 0xffff0000u) + sigmf(G[a][c][2 * i + 1]) * u1;
;             totp[a][c][i] = pack2(t0, t1);
;           }
	s_setprio 1
	v_mfma_f32_32x32x16_bf16 v[48:63], v[96:99], v[104:107], v[48:63]
	ds_read_b128 v[64:67], v128 offset:4608
	ds_read_b128 v[68:71], v129 offset:23040
	ds_read_b128 v[72:75], v128
	ds_read_b128 v[76:79], v128 offset:32
	ds_read_b128 v[80:83], v129 offset:18432
	ds_read_b128 v[84:87], v129 offset:18464
	v_mfma_f32_32x32x16_bf16 v[32:47], v[96:99], v[108:111], v[32:47]
	v_mfma_f32_32x32x16_bf16 v[16:31], v[100:103], v[104:107], v[16:31]
	v_mfma_f32_32x32x16_bf16 v[0:15], v[100:103], v[108:111], v[0:15]
	s_waitcnt lgkmcnt(1)
	v_mfma_f32_32x32x16_bf16 v[48:63], v[72:75], v[80:83], v[48:63]
	v_mfma_f32_32x32x16_bf16 v[32:47], v[72:75], v[68:71], v[32:47]
	v_mfma_f32_32x32x16_bf16 v[16:31], v[64:67], v[80:83], v[16:31]
	v_mfma_f32_32x32x16_bf16 v[0:15], v[64:67], v[68:71], v[0:15]
	ds_read_b128 v[64:67], v128 offset:4640
	ds_read_b128 v[68:71], v129 offset:23072
	s_waitcnt lgkmcnt(2)
	v_mfma_f32_32x32x16_bf16 v[48:63], v[76:79], v[84:87], v[48:63]
	s_waitcnt lgkmcnt(0)
	v_mfma_f32_32x32x16_bf16 v[32:47], v[76:79], v[68:71], v[32:47]
	v_mfma_f32_32x32x16_bf16 v[16:31], v[64:67], v[84:87], v[16:31]
	v_mfma_f32_32x32x16_bf16 v[0:15], v[64:67], v[68:71], v[0:15]
	ds_read_b128 v[64:67], v128 offset:64
	ds_read_b128 v[68:71], v128 offset:4672
	ds_read_b128 v[72:75], v129 offset:18496
	ds_read_b128 v[76:79], v129 offset:23104
	s_waitcnt lgkmcnt(1)
	v_mfma_f32_32x32x16_bf16 v[48:63], v[64:67], v[72:75], v[48:63]
	s_waitcnt lgkmcnt(0)
	v_mfma_f32_32x32x16_bf16 v[32:47], v[64:67], v[76:79], v[32:47]
	v_mfma_f32_32x32x16_bf16 v[16:31], v[68:71], v[72:75], v[16:31]
	v_mfma_f32_32x32x16_bf16 v[0:15], v[68:71], v[76:79], v[0:15]
	ds_read_b128 v[64:67], v128 offset:96
	ds_read_b128 v[68:71], v128 offset:4704
	ds_read_b128 v[72:75], v129 offset:18528
	ds_read_b128 v[76:79], v129 offset:23136
	s_waitcnt lgkmcnt(1)
	v_mfma_f32_32x32x16_bf16 v[48:63], v[64:67], v[72:75], v[48:63]
	s_waitcnt lgkmcnt(0)
	v_mfma_f32_32x32x16_bf16 v[32:47], v[64:67], v[76:79], v[32:47]
	s_nop 9
	v_mul_f32_e32 v48, 0xbfb8aa3b, v48
	v_mul_f32_e32 v49, 0xbfb8aa3b, v49
	v_exp_f32_e32 v48, v48
	v_exp_f32_e32 v49, v49
	v_mul_f32_e32 v50, 0xbfb8aa3b, v50
	v_mul_f32_e32 v51, 0xbfb8aa3b, v51
	v_exp_f32_e32 v50, v50
	v_exp_f32_e32 v51, v51
	ds_read2st64_b32 v[64:65], v140 offset0:144 offset1:148
	v_add_f32_e32 v48, 1.0, v48
	v_add_f32_e32 v49, 1.0, v49
	v_rcp_f32_e32 v48, v48
	v_rcp_f32_e32 v49, v49
	v_add_f32_e32 v50, 1.0, v50
	v_add_f32_e32 v51, 1.0, v51
	v_rcp_f32_e32 v50, v50
	v_rcp_f32_e32 v51, v51
	v_mfma_f32_32x32x16_bf16 v[16:31], v[68:71], v[72:75], v[16:31]
	s_waitcnt lgkmcnt(0)
	v_lshlrev_b32_e32 v66, 16, v64
	v_and_b32_e32 v67, 0xffff0000, v64
	v_lshlrev_b32_e32 v64, 16, v182
	v_mul_f32_e32 v32, 0xbfb8aa3b, v32
	v_mul_f32_e32 v33, 0xbfb8aa3b, v33
	v_exp_f32_e32 v32, v32
	v_exp_f32_e32 v33, v33
	v_mfma_f32_32x32x16_bf16 v[0:15], v[68:71], v[76:79], v[0:15]
	s_setprio 2
	v_lshlrev_b32_e32 v68, 16, v183
	v_and_b32_e32 v69, 0xffff0000, v183
	v_fma_f32 v48, v48, v66, v68
	v_fma_f32 v49, v49, v67, v69
	v_mul_f32_e32 v34, 0xbfb8aa3b, v34
	v_cvt_pk_bf16_f32 v183, v48, v49
	v_lshlrev_b32_e32 v48, 16, v65
	v_and_b32_e32 v49, 0xffff0000, v65
	v_and_b32_e32 v65, 0xffff0000, v182
	v_pk_fma_f32 v[48:49], v[50:51], v[48:49], v[64:65]
	v_lshlrev_b32_e32 v64, 16, v181
	v_cvt_pk_bf16_f32 v182, v48, v49
	ds_read2st64_b32 v[48:49], v140 offset0:152 offset1:156
	v_and_b32_e32 v65, 0xffff0000, v181
	v_mul_f32_e32 v35, 0xbfb8aa3b, v35
	v_exp_f32_e32 v34, v34
	v_exp_f32_e32 v35, v35
	s_waitcnt lgkmcnt(0)
	v_lshlrev_b32_e32 v50, 16, v48
	v_and_b32_e32 v51, 0xffff0000, v48
	v_mul_f32_e32 v48, 0xbfb8aa3b, v52
	v_exp_f32_e32 v48, v48
	v_add_f32_e32 v32, 1.0, v32
	v_add_f32_e32 v33, 1.0, v33
	v_rcp_f32_e32 v32, v32
	v_add_f32_e32 v48, 1.0, v48
	v_rcp_f32_e32 v52, v48
	v_mul_f32_e32 v48, 0xbfb8aa3b, v53
	v_exp_f32_e32 v48, v48
	v_rcp_f32_e32 v33, v33
	v_add_f32_e32 v34, 1.0, v34
	v_add_f32_e32 v35, 1.0, v35
	v_add_f32_e32 v48, 1.0, v48
	v_rcp_f32_e32 v53, v48
	v_lshlrev_b32_e32 v48, 16, v49
	v_and_b32_e32 v49, 0xffff0000, v49
	v_rcp_f32_e32 v34, v34
	v_pk_fma_f32 v[50:51], v[52:53], v[50:51], v[64:65]
	v_mul_f32_e32 v53, 0xbfb8aa3b, v55
	v_cvt_pk_bf16_f32 v181, v50, v51
	v_mul_f32_e32 v51, 0xbfb8aa3b, v54
	v_exp_f32_e32 v51, v51
	v_exp_f32_e32 v53, v53
	v_lshlrev_b32_e32 v50, 16, v180
	v_rcp_f32_e32 v35, v35
	v_add_f32_e32 v51, 1.0, v51
	v_add_f32_e32 v53, 1.0, v53
	v_rcp_f32_e32 v52, v51
	v_rcp_f32_e32 v53, v53
	v_and_b32_e32 v51, 0xffff0000, v180
	v_mul_f32_e32 v16, 0xbfb8aa3b, v16
	v_mul_f32_e32 v17, 0xbfb8aa3b, v17
	v_pk_fma_f32 v[48:49], v[52:53], v[48:49], v[50:51]
	v_lshlrev_b32_e32 v52, 16, v179
	v_cvt_pk_bf16_f32 v180, v48, v49
	ds_read2st64_b32 v[48:49], v140 offset0:160 offset1:164
	v_and_b32_e32 v53, 0xffff0000, v179
	v_exp_f32_e32 v16, v16
	v_exp_f32_e32 v17, v17
	v_mul_f32_e32 v18, 0xbfb8aa3b, v18
	s_waitcnt lgkmcnt(0)
	v_lshlrev_b32_e32 v50, 16, v48
	v_and_b32_e32 v51, 0xffff0000, v48
	v_mul_f32_e32 v48, 0xbfb8aa3b, v56
	v_exp_f32_e32 v48, v48
	v_mul_f32_e32 v19, 0xbfb8aa3b, v19
	v_exp_f32_e32 v18, v18
	v_exp_f32_e32 v19, v19
	v_add_f32_e32 v48, 1.0, v48
	v_rcp_f32_e32 v54, v48
	v_mul_f32_e32 v48, 0xbfb8aa3b, v57
	v_exp_f32_e32 v48, v48
	v_add_f32_e32 v16, 1.0, v16
	v_add_f32_e32 v17, 1.0, v17
	v_rcp_f32_e32 v16, v16
	v_add_f32_e32 v48, 1.0, v48
	v_rcp_f32_e32 v55, v48
	v_lshlrev_b32_e32 v48, 16, v49
	v_and_b32_e32 v49, 0xffff0000, v49
	v_rcp_f32_e32 v17, v17
	v_pk_fma_f32 v[50:51], v[54:55], v[50:51], v[52:53]
	v_mul_f32_e32 v53, 0xbfb8aa3b, v59
	v_cvt_pk_bf16_f32 v179, v50, v51
	v_mul_f32_e32 v51, 0xbfb8aa3b, v58
	v_exp_f32_e32 v51, v51
	v_exp_f32_e32 v53, v53
	v_lshlrev_b32_e32 v50, 16, v177
	v_add_f32_e32 v18, 1.0, v18
	v_add_f32_e32 v51, 1.0, v51
	v_add_f32_e32 v53, 1.0, v53
	v_rcp_f32_e32 v52, v51
	v_rcp_f32_e32 v53, v53
	v_and_b32_e32 v51, 0xffff0000, v177
	v_add_f32_e32 v19, 1.0, v19
	v_rcp_f32_e32 v18, v18
	v_pk_fma_f32 v[48:49], v[52:53], v[48:49], v[50:51]
	v_lshlrev_b32_e32 v52, 16, v178
	v_cvt_pk_bf16_f32 v177, v48, v49
	ds_read2st64_b32 v[48:49], v140 offset0:168 offset1:172
	v_and_b32_e32 v53, 0xffff0000, v178
	v_rcp_f32_e32 v19, v19
	v_mul_f32_e32 v0, 0xbfb8aa3b, v0
	v_mul_f32_e32 v1, 0xbfb8aa3b, v1
	s_waitcnt lgkmcnt(0)
; DI float sigmf(float x) { return __builtin_amdgcn_rcpf(1.f + __expf(-x)); }
; DI void phase_merge(CP p, const Ptrs& w, int l, bf16_t* sA, bf16_t* sB, unsigned* sU) {
;     ...
; #pragma unroll
;       for (int a = 0; a < 2; ++a)
; #pragma unroll
;         for (int c = 0; c < 2; ++c)
; #pragma unroll
;           for (int i = 0; i < 8; ++i) {
;             unsigned uv = sU[((a * 2 + c) * 8 + i) * 256 + tid];
;             float u0 = __uint_as_float(uv << 16), u1 = __uint_as_float(uv & 0xffff0000u);
;             const unsigned tv = totp[a][c][i];
;             float t0 = __uint_as_float(tv << 16) + sigmf(G[a][c][2 * i]) * u0;
;             float t1 = __uint_as_float(tv & 0xffff0000u) + sigmf(G[a][c][2 * i + 1]) * u1;
;             totp[a][c][i] = pack2(t0, t1);
;           }
	v_lshlrev_b32_e32 v50, 16, v48
	v_and_b32_e32 v51, 0xffff0000, v48
	v_mul_f32_e32 v48, 0xbfb8aa3b, v60
	v_exp_f32_e32 v48, v48
	v_exp_f32_e32 v0, v0
	v_exp_f32_e32 v1, v1
	v_mul_f32_e32 v2, 0xbfb8aa3b, v2
	v_add_f32_e32 v48, 1.0, v48
	v_rcp_f32_e32 v54, v48
	v_mul_f32_e32 v48, 0xbfb8aa3b, v61
	v_exp_f32_e32 v48, v48
	v_mul_f32_e32 v3, 0xbfb8aa3b, v3
	v_exp_f32_e32 v2, v2
	v_exp_f32_e32 v3, v3
	v_add_f32_e32 v48, 1.0, v48
	v_rcp_f32_e32 v55, v48
	v_lshlrev_b32_e32 v48, 16, v49
	v_and_b32_e32 v49, 0xffff0000, v49
	v_add_f32_e32 v0, 1.0, v0
	v_pk_fma_f32 v[50:51], v[54:55], v[50:51], v[52:53]
	v_mul_f32_e32 v53, 0xbfb8aa3b, v63
	v_cvt_pk_bf16_f32 v178, v50, v51
	v_mul_f32_e32 v51, 0xbfb8aa3b, v62
	v_exp_f32_e32 v51, v51
	v_exp_f32_e32 v53, v53
	v_lshlrev_b32_e32 v50, 16, v173
	v_add_f32_e32 v1, 1.0, v1
	v_add_f32_e32 v51, 1.0, v51
	v_add_f32_e32 v53, 1.0, v53
	v_rcp_f32_e32 v52, v51
	v_rcp_f32_e32 v53, v53
	v_and_b32_e32 v51, 0xffff0000, v173
	v_rcp_f32_e32 v0, v0
	v_rcp_f32_e32 v1, v1
	v_pk_fma_f32 v[48:49], v[52:53], v[48:49], v[50:51]
	v_lshlrev_b32_e32 v52, 16, v176
	v_cvt_pk_bf16_f32 v173, v48, v49
	ds_read2st64_b32 v[48:49], v140 offset0:176 offset1:180
	v_and_b32_e32 v53, 0xffff0000, v176
	v_add_f32_e32 v2, 1.0, v2
	v_add_f32_e32 v3, 1.0, v3
	v_rcp_f32_e32 v2, v2
	s_waitcnt lgkmcnt(0)
	v_lshlrev_b32_e32 v50, 16, v48
	v_and_b32_e32 v51, 0xffff0000, v48
	v_pk_fma_f32 v[32:33], v[32:33], v[50:51], v[52:53]
	v_lshlrev_b32_e32 v48, 16, v170
	v_cvt_pk_bf16_f32 v176, v32, v33
	v_lshlrev_b32_e32 v32, 16, v49
	v_and_b32_e32 v33, 0xffff0000, v49
	v_and_b32_e32 v49, 0xffff0000, v170
	v_pk_fma_f32 v[32:33], v[34:35], v[32:33], v[48:49]
	v_lshlrev_b32_e32 v48, 16, v175
	v_cvt_pk_bf16_f32 v170, v32, v33
	ds_read2st64_b32 v[32:33], v140 offset0:184 offset1:188
	v_and_b32_e32 v49, 0xffff0000, v175
	v_rcp_f32_e32 v3, v3
	s_waitcnt lgkmcnt(0)
	v_lshlrev_b32_e32 v34, 16, v32
	v_and_b32_e32 v35, 0xffff0000, v32
	v_mul_f32_e32 v32, 0xbfb8aa3b, v36
	v_exp_f32_e32 v32, v32
	s_nop 0
	v_add_f32_e32 v32, 1.0, v32
	v_rcp_f32_e32 v36, v32
	v_mul_f32_e32 v32, 0xbfb8aa3b, v37
	v_exp_f32_e32 v32, v32
	s_nop 0
	v_add_f32_e32 v32, 1.0, v32
	v_rcp_f32_e32 v37, v32
	v_lshlrev_b32_e32 v32, 16, v33
	v_and_b32_e32 v33, 0xffff0000, v33
	v_pk_fma_f32 v[34:35], v[36:37], v[34:35], v[48:49]
	s_nop 0
	v_cvt_pk_bf16_f32 v175, v34, v35
	v_mul_f32_e32 v35, 0xbfb8aa3b, v38
	v_mul_f32_e32 v37, 0xbfb8aa3b, v39
	v_exp_f32_e32 v35, v35
	v_exp_f32_e32 v37, v37
	v_lshlrev_b32_e32 v34, 16, v174
	v_add_f32_e32 v35, 1.0, v35
	v_add_f32_e32 v37, 1.0, v37
	v_rcp_f32_e32 v36, v35
	v_rcp_f32_e32 v37, v37
	v_and_b32_e32 v35, 0xffff0000, v174
	v_pk_fma_f32 v[32:33], v[36:37], v[32:33], v[34:35]
	s_nop 0
	v_cvt_pk_bf16_f32 v174, v32, v33
	ds_read2st64_b32 v[32:33], v140 offset0:192 offset1:196
	v_lshlrev_b32_e32 v36, 16, v172
	v_and_b32_e32 v37, 0xffff0000, v172
	s_waitcnt lgkmcnt(0)
	v_lshlrev_b32_e32 v34, 16, v32
	v_and_b32_e32 v35, 0xffff0000, v32
	v_mul_f32_e32 v32, 0xbfb8aa3b, v40
	v_exp_f32_e32 v32, v32
	s_nop 0
	v_add_f32_e32 v32, 1.0, v32
	v_rcp_f32_e32 v38, v32
	v_mul_f32_e32 v32, 0xbfb8aa3b, v41
	v_exp_f32_e32 v32, v32
	s_nop 0
	v_add_f32_e32 v32, 1.0, v32
	v_rcp_f32_e32 v39, v32
	v_lshlrev_b32_e32 v32, 16, v33
	v_and_b32_e32 v33, 0xffff0000, v33
	v_pk_fma_f32 v[34:35], v[38:39], v[34:35], v[36:37]
	s_nop 0
	v_cvt_pk_bf16_f32 v172, v34, v35
	v_mul_f32_e32 v35, 0xbfb8aa3b, v42
	v_mul_f32_e32 v37, 0xbfb8aa3b, v43
	v_exp_f32_e32 v35, v35
	v_exp_f32_e32 v37, v37
	v_lshlrev_b32_e32 v34, 16, v171
	v_add_f32_e32 v35, 1.0, v35
	v_add_f32_e32 v37, 1.0, v37
	v_rcp_f32_e32 v36, v35
	v_rcp_f32_e32 v37, v37
	v_and_b32_e32 v35, 0xffff0000, v171
	v_pk_fma_f32 v[32:33], v[36:37], v[32:33], v[34:35]
	s_nop 0
	v_cvt_pk_bf16_f32 v171, v32, v33
	ds_read2st64_b32 v[32:33], v140 offset0:200 offset1:204
	v_lshlrev_b32_e32 v36, 16, v169
	v_and_b32_e32 v37, 0xffff0000, v169
	s_waitcnt lgkmcnt(0)
	v_lshlrev_b32_e32 v34, 16, v32
	v_and_b32_e32 v35, 0xffff0000, v32
	v_mul_f32_e32 v32, 0xbfb8aa3b, v44
	v_exp_f32_e32 v32, v32
	s_nop 0
	v_add_f32_e32 v32, 1.0, v32
	v_rcp_f32_e32 v38, v32
	v_mul_f32_e32 v32, 0xbfb8aa3b, v45
	v_exp_f32_e32 v32, v32
	s_nop 0
	v_add_f32_e32 v32, 1.0, v32
	v_rcp_f32_e32 v39, v32
	v_lshlrev_b32_e32 v32, 16, v33
	v_and_b32_e32 v33, 0xffff0000, v33
	v_pk_fma_f32 v[34:35], v[38:39], v[34:35], v[36:37]
	s_nop 0
	v_cvt_pk_bf16_f32 v169, v34, v35
	v_mul_f32_e32 v35, 0xbfb8aa3b, v46
	v_mul_f32_e32 v37, 0xbfb8aa3b, v47
	v_exp_f32_e32 v35, v35
	v_exp_f32_e32 v37, v37
	v_lshlrev_b32_e32 v34, 16, v168
	v_add_f32_e32 v35, 1.0, v35
	v_add_f32_e32 v37, 1.0, v37
	v_rcp_f32_e32 v36, v35
	v_rcp_f32_e32 v37, v37
	v_and_b32_e32 v35, 0xffff0000, v168
	v_pk_fma_f32 v[32:33], v[36:37], v[32:33], v[34:35]
	s_nop 0
	v_cvt_pk_bf16_f32 v168, v32, v33
	ds_read2st64_b32 v[32:33], v140 offset0:208 offset1:212
	v_lshlrev_b32_e32 v36, 16, v167
	v_and_b32_e32 v37, 0xffff0000, v167
	s_waitcnt lgkmcnt(0)
	v_lshlrev_b32_e32 v34, 16, v32
	v_and_b32_e32 v35, 0xffff0000, v32
	v_pk_fma_f32 v[16:17], v[16:17], v[34:35], v[36:37]
	v_lshlrev_b32_e32 v32, 16, v164
	v_cvt_pk_bf16_f32 v167, v16, v17
	v_lshlrev_b32_e32 v16, 16, v33
	v_and_b32_e32 v17, 0xffff0000, v33
	v_and_b32_e32 v33, 0xffff0000, v164
	v_pk_fma_f32 v[16:17], v[18:19], v[16:17], v[32:33]
	v_lshlrev_b32_e32 v32, 16, v163
	v_cvt_pk_bf16_f32 v164, v16, v17
	ds_read2st64_b32 v[16:17], v140 offset0:216 offset1:220
	v_and_b32_e32 v33, 0xffff0000, v163
	s_waitcnt lgkmcnt(0)
; DI float sigmf(float x) { return __builtin_amdgcn_rcpf(1.f + __expf(-x)); }
; DI void phase_merge(CP p, const Ptrs& w, int l, bf16_t* sA, bf16_t* sB, unsigned* sU) {
;     ...
; #pragma unroll
;       for (int a = 0; a < 2; ++a)
; #pragma unroll
;         for (int c = 0; c < 2; ++c)
; #pragma unroll
;           for (int i = 0; i < 8; ++i) {
;             unsigned uv = sU[((a * 2 + c) * 8 + i) * 256 + tid];
;             float u0 = __uint_as_float(uv << 16), u1 = __uint_as_float(uv & 0xffff0000u);
;             const unsigned tv = totp[a][c][i];
;             float t0 = __uint_as_float(tv << 16) + sigmf(G[a][c][2 * i]) * u0;
;             float t1 = __uint_as_float(tv & 0xffff0000u) + sigmf(G[a][c][2 * i + 1]) * u1;
;             totp[a][c][i] = pack2(t0, t1);
;           }
	v_lshlrev_b32_e32 v18, 16, v16
	v_and_b32_e32 v19, 0xffff0000, v16
	v_mul_f32_e32 v16, 0xbfb8aa3b, v20
	v_exp_f32_e32 v16, v16
	s_nop 0
	v_add_f32_e32 v16, 1.0, v16
	v_rcp_f32_e32 v20, v16
	v_mul_f32_e32 v16, 0xbfb8aa3b, v21
	v_exp_f32_e32 v16, v16
	s_nop 0
	v_add_f32_e32 v16, 1.0, v16
	v_rcp_f32_e32 v21, v16
	v_lshlrev_b32_e32 v16, 16, v17
	v_and_b32_e32 v17, 0xffff0000, v17
	v_pk_fma_f32 v[18:19], v[20:21], v[18:19], v[32:33]
	s_nop 0
	v_cvt_pk_bf16_f32 v163, v18, v19
	v_mul_f32_e32 v19, 0xbfb8aa3b, v22
	v_mul_f32_e32 v21, 0xbfb8aa3b, v23
	v_exp_f32_e32 v19, v19
	v_exp_f32_e32 v21, v21
	v_lshlrev_b32_e32 v18, 16, v161
	v_add_f32_e32 v19, 1.0, v19
	v_add_f32_e32 v21, 1.0, v21
	v_rcp_f32_e32 v20, v19
	v_rcp_f32_e32 v21, v21
	v_and_b32_e32 v19, 0xffff0000, v161
	v_pk_fma_f32 v[16:17], v[20:21], v[16:17], v[18:19]
	s_nop 0
	v_cvt_pk_bf16_f32 v161, v16, v17
	ds_read2st64_b32 v[16:17], v140 offset0:224 offset1:228
	v_lshlrev_b32_e32 v20, 16, v155
	v_and_b32_e32 v21, 0xffff0000, v155
	s_waitcnt lgkmcnt(0)
	v_lshlrev_b32_e32 v18, 16, v16
	v_and_b32_e32 v19, 0xffff0000, v16
	v_mul_f32_e32 v16, 0xbfb8aa3b, v24
	v_exp_f32_e32 v16, v16
	s_nop 0
	v_add_f32_e32 v16, 1.0, v16
	v_rcp_f32_e32 v22, v16
	v_mul_f32_e32 v16, 0xbfb8aa3b, v25
	v_exp_f32_e32 v16, v16
	s_nop 0
	v_add_f32_e32 v16, 1.0, v16
	v_rcp_f32_e32 v23, v16
	v_lshlrev_b32_e32 v16, 16, v17
	v_and_b32_e32 v17, 0xffff0000, v17
	v_pk_fma_f32 v[18:19], v[22:23], v[18:19], v[20:21]
	s_nop 0
	v_cvt_pk_bf16_f32 v155, v18, v19
	v_mul_f32_e32 v19, 0xbfb8aa3b, v26
	v_mul_f32_e32 v21, 0xbfb8aa3b, v27
	v_exp_f32_e32 v19, v19
	v_exp_f32_e32 v21, v21
	v_lshlrev_b32_e32 v18, 16, v154
	v_add_f32_e32 v19, 1.0, v19
	v_add_f32_e32 v21, 1.0, v21
	v_rcp_f32_e32 v20, v19
	v_rcp_f32_e32 v21, v21
	v_and_b32_e32 v19, 0xffff0000, v154
	v_pk_fma_f32 v[16:17], v[20:21], v[16:17], v[18:19]
	s_nop 0
	v_cvt_pk_bf16_f32 v154, v16, v17
	ds_read2st64_b32 v[16:17], v140 offset0:232 offset1:236
	v_lshlrev_b32_e32 v20, 16, v153
	v_and_b32_e32 v21, 0xffff0000, v153
	s_waitcnt lgkmcnt(0)
	v_lshlrev_b32_e32 v18, 16, v16
	v_and_b32_e32 v19, 0xffff0000, v16
	v_mul_f32_e32 v16, 0xbfb8aa3b, v28
	v_exp_f32_e32 v16, v16
	s_nop 0
	v_add_f32_e32 v16, 1.0, v16
	v_rcp_f32_e32 v22, v16
	v_mul_f32_e32 v16, 0xbfb8aa3b, v29
	v_exp_f32_e32 v16, v16
	s_nop 0
	v_add_f32_e32 v16, 1.0, v16
	v_rcp_f32_e32 v23, v16
	v_lshlrev_b32_e32 v16, 16, v17
	v_and_b32_e32 v17, 0xffff0000, v17
	v_pk_fma_f32 v[18:19], v[22:23], v[18:19], v[20:21]
	s_nop 0
	v_cvt_pk_bf16_f32 v153, v18, v19
	v_mul_f32_e32 v19, 0xbfb8aa3b, v30
	v_mul_f32_e32 v21, 0xbfb8aa3b, v31
	v_exp_f32_e32 v19, v19
	v_exp_f32_e32 v21, v21
	v_lshlrev_b32_e32 v18, 16, v152
	v_add_f32_e32 v19, 1.0, v19
	v_add_f32_e32 v21, 1.0, v21
	v_rcp_f32_e32 v20, v19
	v_rcp_f32_e32 v21, v21
	v_and_b32_e32 v19, 0xffff0000, v152
	v_pk_fma_f32 v[16:17], v[20:21], v[16:17], v[18:19]
	s_nop 0
	v_cvt_pk_bf16_f32 v152, v16, v17
	ds_read2st64_b32 v[16:17], v140 offset0:240 offset1:244
	v_lshlrev_b32_e32 v20, 16, v151
	v_and_b32_e32 v21, 0xffff0000, v151
	s_waitcnt lgkmcnt(0)
	v_lshlrev_b32_e32 v18, 16, v16
	v_and_b32_e32 v19, 0xffff0000, v16
	v_pk_fma_f32 v[0:1], v[0:1], v[18:19], v[20:21]
	v_lshlrev_b32_e32 v16, 16, v150
	v_cvt_pk_bf16_f32 v151, v0, v1
	v_lshlrev_b32_e32 v0, 16, v17
	v_and_b32_e32 v1, 0xffff0000, v17
	v_and_b32_e32 v17, 0xffff0000, v150
	v_pk_fma_f32 v[0:1], v[2:3], v[0:1], v[16:17]
	v_lshlrev_b32_e32 v16, 16, v149
	v_cvt_pk_bf16_f32 v150, v0, v1
	ds_read2st64_b32 v[0:1], v140 offset0:248 offset1:252
	v_and_b32_e32 v17, 0xffff0000, v149
	s_waitcnt lgkmcnt(0)
	v_lshlrev_b32_e32 v2, 16, v0
	v_and_b32_e32 v3, 0xffff0000, v0
	v_mul_f32_e32 v0, 0xbfb8aa3b, v4
	v_exp_f32_e32 v0, v0
	s_nop 0
	v_add_f32_e32 v0, 1.0, v0
	v_rcp_f32_e32 v4, v0
	v_mul_f32_e32 v0, 0xbfb8aa3b, v5
	v_exp_f32_e32 v0, v0
	s_nop 0
	v_add_f32_e32 v0, 1.0, v0
	v_rcp_f32_e32 v5, v0
	v_lshlrev_b32_e32 v0, 16, v1
	v_and_b32_e32 v1, 0xffff0000, v1
	v_pk_fma_f32 v[2:3], v[4:5], v[2:3], v[16:17]
	s_nop 0
	v_cvt_pk_bf16_f32 v149, v2, v3
	v_mul_f32_e32 v3, 0xbfb8aa3b, v6
	v_mul_f32_e32 v5, 0xbfb8aa3b, v7
	v_exp_f32_e32 v3, v3
	v_exp_f32_e32 v5, v5
	v_lshlrev_b32_e32 v2, 16, v148
	v_add_f32_e32 v3, 1.0, v3
	v_add_f32_e32 v5, 1.0, v5
	v_rcp_f32_e32 v4, v3
	v_rcp_f32_e32 v5, v5
	v_and_b32_e32 v3, 0xffff0000, v148
	v_pk_fma_f32 v[0:1], v[4:5], v[0:1], v[2:3]
	s_nop 0
	v_cvt_pk_bf16_f32 v148, v0, v1
	ds_read2st64_b32 v[0:1], v141 offset0:112 offset1:116
	v_lshlrev_b32_e32 v4, 16, v147
	v_and_b32_e32 v5, 0xffff0000, v147
	s_waitcnt lgkmcnt(0)
	v_lshlrev_b32_e32 v2, 16, v0
	v_and_b32_e32 v3, 0xffff0000, v0
	v_mul_f32_e32 v0, 0xbfb8aa3b, v8
	v_exp_f32_e32 v0, v0
	s_nop 0
	v_add_f32_e32 v0, 1.0, v0
	v_rcp_f32_e32 v6, v0
	v_mul_f32_e32 v0, 0xbfb8aa3b, v9
	v_exp_f32_e32 v0, v0
	s_nop 0
	v_add_f32_e32 v0, 1.0, v0
	v_rcp_f32_e32 v7, v0
	v_lshlrev_b32_e32 v0, 16, v1
	v_and_b32_e32 v1, 0xffff0000, v1
	v_pk_fma_f32 v[2:3], v[6:7], v[2:3], v[4:5]
	s_nop 0
	v_cvt_pk_bf16_f32 v147, v2, v3
	v_mul_f32_e32 v3, 0xbfb8aa3b, v10
	v_mul_f32_e32 v5, 0xbfb8aa3b, v11
	v_exp_f32_e32 v3, v3
	v_exp_f32_e32 v5, v5
	v_lshlrev_b32_e32 v2, 16, v146
	v_add_f32_e32 v3, 1.0, v3
	v_add_f32_e32 v5, 1.0, v5
	v_rcp_f32_e32 v4, v3
	v_rcp_f32_e32 v5, v5
	v_and_b32_e32 v3, 0xffff0000, v146
	v_pk_fma_f32 v[0:1], v[4:5], v[0:1], v[2:3]
	s_nop 0
	v_cvt_pk_bf16_f32 v146, v0, v1
	ds_read2st64_b32 v[0:1], v141 offset0:120 offset1:124
	v_lshlrev_b32_e32 v4, 16, v145
	v_and_b32_e32 v5, 0xffff0000, v145
	s_waitcnt lgkmcnt(0)
	v_lshlrev_b32_e32 v2, 16, v0
	v_and_b32_e32 v3, 0xffff0000, v0
	v_mul_f32_e32 v0, 0xbfb8aa3b, v12
	v_exp_f32_e32 v0, v0
	s_nop 0
	v_add_f32_e32 v0, 1.0, v0
	v_rcp_f32_e32 v6, v0
	v_mul_f32_e32 v0, 0xbfb8aa3b, v13
	v_exp_f32_e32 v0, v0
	s_nop 0
	v_add_f32_e32 v0, 1.0, v0
	v_rcp_f32_e32 v7, v0
	v_lshlrev_b32_e32 v0, 16, v1
	v_and_b32_e32 v1, 0xffff0000, v1
	v_pk_fma_f32 v[2:3], v[6:7], v[2:3], v[4:5]
	s_nop 0
	v_cvt_pk_bf16_f32 v145, v2, v3
	v_mul_f32_e32 v3, 0xbfb8aa3b, v14
	v_mul_f32_e32 v5, 0xbfb8aa3b, v15
	v_exp_f32_e32 v3, v3
	v_exp_f32_e32 v5, v5
	v_lshlrev_b32_e32 v2, 16, v144
	v_add_f32_e32 v3, 1.0, v3
	v_add_f32_e32 v5, 1.0, v5
	v_rcp_f32_e32 v4, v3
	v_rcp_f32_e32 v5, v5
	v_and_b32_e32 v3, 0xffff0000, v144
	v_pk_fma_f32 v[0:1], v[4:5], v[0:1], v[2:3]
	s_nop 0
	v_cvt_pk_bf16_f32 v144, v0, v1
	s_cbranch_scc0 .LBB0_871
; DI int crow(int i, int h) { return (i & 3) + 8 * (i >> 2) + 4 * h; }
; DI void phase_merge(CP p, const Ptrs& w, int l, bf16_t* sA, bf16_t* sB, unsigned* sU) {
;     ...
;     bf16_t* dst = w.R2;
; #pragma unroll
;     for (int mi = 0; mi < 2; ++mi)
; #pragma unroll
;       for (int ni = 0; ni < 2; ++ni)
; #pragma unroll
;         for (int i = 0; i < 16; ++i) {
;           int row = m0 + wm * 64 + mi * 32 + crow(i, h), col = n0 + wn * 64 + ni * 32 + r;
;           const unsigned tv = totp[mi][ni][i >> 1];
;           dst[(size_t)row * 2048 + col] = (bf16_t)((i & 1) ? (tv >> 16) : (tv & 0xffffu));
;         }
	v_add_u32_e32 v0, s38, v142
	v_or_b32_e32 v2, s72, v143
	v_or_b32_e32 v6, 1, v0
	v_or_b32_e32 v8, 2, v0
	v_or_b32_e32 v10, 3, v0
	v_or_b32_e32 v12, 8, v0
	v_or_b32_e32 v14, 9, v0
	v_or_b32_e32 v16, 10, v0
	v_or_b32_e32 v18, 11, v0
	v_or_b32_e32 v20, 16, v0
	v_or_b32_e32 v22, 17, v0
	v_or_b32_e32 v24, 18, v0
	v_or_b32_e32 v26, 19, v0
	v_or_b32_e32 v28, 24, v0
	v_or_b32_e32 v30, 25, v0
	v_or_b32_e32 v32, 26, v0
	v_or_b32_e32 v34, 27, v0
	v_ashrrev_i32_e32 v3, 31, v2
	v_ashrrev_i32_e32 v1, 31, v0
	v_ashrrev_i32_e32 v7, 31, v6
	v_ashrrev_i32_e32 v9, 31, v8
	v_ashrrev_i32_e32 v11, 31, v10
	v_ashrrev_i32_e32 v13, 31, v12
	v_ashrrev_i32_e32 v15, 31, v14
	v_ashrrev_i32_e32 v17, 31, v16
	v_ashrrev_i32_e32 v19, 31, v18
	v_ashrrev_i32_e32 v21, 31, v20
	v_ashrrev_i32_e32 v23, 31, v22
	v_ashrrev_i32_e32 v25, 31, v24
	v_ashrrev_i32_e32 v27, 31, v26
	v_ashrrev_i32_e32 v29, 31, v28
	v_ashrrev_i32_e32 v31, 31, v30
	v_ashrrev_i32_e32 v33, 31, v32
	v_ashrrev_i32_e32 v35, 31, v34
	v_lshl_add_u64 v[2:3], v[2:3], 1, s[10:11]
	v_lshlrev_b64 v[4:5], 12, v[0:1]
	v_lshlrev_b64 v[6:7], 12, v[6:7]
	v_lshlrev_b64 v[8:9], 12, v[8:9]
	v_lshlrev_b64 v[10:11], 12, v[10:11]
	v_lshlrev_b64 v[12:13], 12, v[12:13]
	v_lshlrev_b64 v[14:15], 12, v[14:15]
	v_lshlrev_b64 v[16:17], 12, v[16:17]
	v_lshlrev_b64 v[18:19], 12, v[18:19]
	v_lshlrev_b64 v[20:21], 12, v[20:21]
	v_lshlrev_b64 v[22:23], 12, v[22:23]
	v_lshlrev_b64 v[24:25], 12, v[24:25]
	v_lshlrev_b64 v[26:27], 12, v[26:27]
	v_lshlrev_b64 v[28:29], 12, v[28:29]
	v_lshlrev_b64 v[30:31], 12, v[30:31]
	v_lshlrev_b64 v[32:33], 12, v[32:33]
	v_lshlrev_b64 v[34:35], 12, v[34:35]
	v_lshl_add_u64 v[4:5], v[2:3], 0, v[4:5]
	v_lshl_add_u64 v[6:7], v[2:3], 0, v[6:7]
	v_lshl_add_u64 v[8:9], v[2:3], 0, v[8:9]
	v_lshl_add_u64 v[10:11], v[2:3], 0, v[10:11]
	v_lshl_add_u64 v[12:13], v[2:3], 0, v[12:13]
	v_lshl_add_u64 v[14:15], v[2:3], 0, v[14:15]
	v_lshl_add_u64 v[16:17], v[2:3], 0, v[16:17]
	v_lshl_add_u64 v[18:19], v[2:3], 0, v[18:19]
	v_lshl_add_u64 v[20:21], v[2:3], 0, v[20:21]
	v_lshl_add_u64 v[22:23], v[2:3], 0, v[22:23]
	v_lshl_add_u64 v[24:25], v[2:3], 0, v[24:25]
	v_lshl_add_u64 v[26:27], v[2:3], 0, v[26:27]
	v_lshl_add_u64 v[28:29], v[2:3], 0, v[28:29]
	v_lshl_add_u64 v[30:31], v[2:3], 0, v[30:31]
	v_lshl_add_u64 v[32:33], v[2:3], 0, v[32:33]
	v_lshl_add_u64 v[34:35], v[2:3], 0, v[34:35]
	global_store_short v[4:5], v183, off
	global_store_short_d16_hi v[6:7], v183, off
	global_store_short v[8:9], v182, off
	global_store_short_d16_hi v[10:11], v182, off
	global_store_short v[12:13], v181, off
	global_store_short_d16_hi v[14:15], v181, off
	global_store_short v[16:17], v180, off
	global_store_short_d16_hi v[18:19], v180, off
	global_store_short v[20:21], v179, off
	global_store_short_d16_hi v[22:23], v179, off
	global_store_short v[24:25], v177, off
	global_store_short_d16_hi v[26:27], v177, off
	global_store_short v[28:29], v178, off
	global_store_short_d16_hi v[30:31], v178, off
	global_store_short v[32:33], v173, off
	global_store_short_d16_hi v[34:35], v173, off
	global_store_short v[4:5], v176, off offset:64
	global_store_short_d16_hi v[6:7], v176, off offset:64
	global_store_short v[8:9], v170, off offset:64
	global_store_short_d16_hi v[10:11], v170, off offset:64
	global_store_short v[12:13], v175, off offset:64
	global_store_short_d16_hi v[14:15], v175, off offset:64
	global_store_short v[16:17], v174, off offset:64
	global_store_short_d16_hi v[18:19], v174, off offset:64
	global_store_short v[20:21], v172, off offset:64
	global_store_short_d16_hi v[22:23], v172, off offset:64
	global_store_short v[24:25], v171, off offset:64
	global_store_short_d16_hi v[26:27], v171, off offset:64
	global_store_short v[28:29], v169, off offset:64
	global_store_short_d16_hi v[30:31], v169, off offset:64
	global_store_short v[32:33], v168, off offset:64
	global_store_short_d16_hi v[34:35], v168, off offset:64
; DI int crow(int i, int h) { return (i & 3) + 8 * (i >> 2) + 4 * h; }
; DI void phase_merge(CP p, const Ptrs& w, int l, bf16_t* sA, bf16_t* sB, unsigned* sU) {
;     ...
;   for (int kk = 0; kk < nrounds; ++kk) {
;     ...
;     bf16_t* dst = w.R2;
; #pragma unroll
;     for (int mi = 0; mi < 2; ++mi)
; #pragma unroll
;       for (int ni = 0; ni < 2; ++ni)
; #pragma unroll
;         for (int i = 0; i < 16; ++i) {
;           int row = m0 + wm * 64 + mi * 32 + crow(i, h), col = n0 + wn * 64 + ni * 32 + r;
;           const unsigned tv = totp[mi][ni][i >> 1];
;           dst[(size_t)row * 2048 + col] = (bf16_t)((i & 1) ? (tv >> 16) : (tv & 0xffffu));
;         }
	v_or_b32_e32 v4, 32, v0
	v_or_b32_e32 v6, 33, v0
	v_or_b32_e32 v8, 34, v0
	v_or_b32_e32 v10, 35, v0
	v_or_b32_e32 v12, 40, v0
	v_or_b32_e32 v14, 41, v0
	v_or_b32_e32 v16, 42, v0
	v_or_b32_e32 v18, 43, v0
	v_or_b32_e32 v20, 48, v0
	v_or_b32_e32 v22, 49, v0
	v_or_b32_e32 v24, 50, v0
	v_or_b32_e32 v26, 51, v0
	v_or_b32_e32 v28, 56, v0
	v_or_b32_e32 v30, 57, v0
	v_or_b32_e32 v32, 58, v0
	v_or_b32_e32 v0, 59, v0
	v_ashrrev_i32_e32 v5, 31, v4
	v_ashrrev_i32_e32 v7, 31, v6
	v_ashrrev_i32_e32 v9, 31, v8
	v_ashrrev_i32_e32 v11, 31, v10
	v_ashrrev_i32_e32 v13, 31, v12
	v_ashrrev_i32_e32 v15, 31, v14
	v_ashrrev_i32_e32 v17, 31, v16
	v_ashrrev_i32_e32 v19, 31, v18
	v_ashrrev_i32_e32 v21, 31, v20
	v_ashrrev_i32_e32 v23, 31, v22
	v_ashrrev_i32_e32 v25, 31, v24
	v_ashrrev_i32_e32 v27, 31, v26
	v_ashrrev_i32_e32 v29, 31, v28
	v_ashrrev_i32_e32 v31, 31, v30
	v_ashrrev_i32_e32 v33, 31, v32
	v_ashrrev_i32_e32 v1, 31, v0
	v_lshlrev_b64 v[4:5], 12, v[4:5]
	v_lshlrev_b64 v[6:7], 12, v[6:7]
	v_lshlrev_b64 v[8:9], 12, v[8:9]
	v_lshlrev_b64 v[10:11], 12, v[10:11]
	v_lshlrev_b64 v[12:13], 12, v[12:13]
	v_lshlrev_b64 v[14:15], 12, v[14:15]
	v_lshlrev_b64 v[16:17], 12, v[16:17]
	v_lshlrev_b64 v[18:19], 12, v[18:19]
	v_lshlrev_b64 v[20:21], 12, v[20:21]
	v_lshlrev_b64 v[22:23], 12, v[22:23]
	v_lshlrev_b64 v[24:25], 12, v[24:25]
	v_lshlrev_b64 v[26:27], 12, v[26:27]
	v_lshlrev_b64 v[28:29], 12, v[28:29]
	v_lshlrev_b64 v[30:31], 12, v[30:31]
	v_lshlrev_b64 v[32:33], 12, v[32:33]
	v_lshlrev_b64 v[0:1], 12, v[0:1]
	v_lshl_add_u64 v[4:5], v[2:3], 0, v[4:5]
	v_lshl_add_u64 v[6:7], v[2:3], 0, v[6:7]
	v_lshl_add_u64 v[8:9], v[2:3], 0, v[8:9]
	v_lshl_add_u64 v[10:11], v[2:3], 0, v[10:11]
	v_lshl_add_u64 v[12:13], v[2:3], 0, v[12:13]
	v_lshl_add_u64 v[14:15], v[2:3], 0, v[14:15]
	v_lshl_add_u64 v[16:17], v[2:3], 0, v[16:17]
	v_lshl_add_u64 v[18:19], v[2:3], 0, v[18:19]
	v_lshl_add_u64 v[20:21], v[2:3], 0, v[20:21]
	v_lshl_add_u64 v[22:23], v[2:3], 0, v[22:23]
	v_lshl_add_u64 v[24:25], v[2:3], 0, v[24:25]
	v_lshl_add_u64 v[26:27], v[2:3], 0, v[26:27]
	v_lshl_add_u64 v[28:29], v[2:3], 0, v[28:29]
	v_lshl_add_u64 v[30:31], v[2:3], 0, v[30:31]
	v_lshl_add_u64 v[32:33], v[2:3], 0, v[32:33]
	v_lshl_add_u64 v[0:1], v[2:3], 0, v[0:1]
	global_store_short v[4:5], v167, off
	global_store_short_d16_hi v[6:7], v167, off
	global_store_short v[8:9], v164, off
	global_store_short_d16_hi v[10:11], v164, off
	global_store_short v[12:13], v163, off
	global_store_short_d16_hi v[14:15], v163, off
	global_store_short v[16:17], v161, off
	global_store_short_d16_hi v[18:19], v161, off
	global_store_short v[20:21], v155, off
	global_store_short_d16_hi v[22:23], v155, off
	global_store_short v[24:25], v154, off
	global_store_short_d16_hi v[26:27], v154, off
	global_store_short v[28:29], v153, off
	global_store_short_d16_hi v[30:31], v153, off
	global_store_short v[32:33], v152, off
	global_store_short_d16_hi v[0:1], v152, off
	global_store_short v[4:5], v151, off offset:64
	global_store_short_d16_hi v[6:7], v151, off offset:64
	global_store_short v[8:9], v150, off offset:64
	global_store_short_d16_hi v[10:11], v150, off offset:64
	global_store_short v[12:13], v149, off offset:64
	global_store_short_d16_hi v[14:15], v149, off offset:64
	global_store_short v[16:17], v148, off offset:64
	global_store_short_d16_hi v[18:19], v148, off offset:64
	global_store_short v[20:21], v147, off offset:64
	global_store_short_d16_hi v[22:23], v147, off offset:64
	global_store_short v[24:25], v146, off offset:64
	global_store_short_d16_hi v[26:27], v146, off offset:64
	global_store_short v[28:29], v145, off offset:64
	global_store_short_d16_hi v[30:31], v145, off offset:64
	global_store_short v[32:33], v144, off offset:64
	global_store_short_d16_hi v[0:1], v144, off offset:64
	s_add_i32 s69, s69, 1
	s_cmp_lg_u32 s69, s60
	s_mov_b32 s42, s71
	s_cbranch_scc1 .LBB0_861

; DI void xcd_barrier_complete(unsigned* bar, unsigned x, unsigned& nloc, unsigned& nx) {
;   const unsigned G = gridDim.x * gridDim.y * gridDim.z;
; DI void xcd_barrier(const XcdBarrier& b) {
;   asm volatile("s_waitcnt vmcnt(0)" ::: "memory");
;   __syncthreads();
;   if (threadIdx.x == 0) {
;     unsigned* bar = b.bar;
;     __builtin_amdgcn_s_waitcnt(0);
;     unsigned nloc = b.st[0], nx = b.st[1];
;     if (nloc == 0u) { xcd_barrier_complete(bar, b.x, nloc, nx); b.st[0] = nloc; b.st[1] = nx; }
.LBB0_887:
	s_setprio 0
	s_waitcnt vmcnt(0)
	s_waitcnt vmcnt(63) expcnt(7) lgkmcnt(15)
	s_barrier
	s_mov_b64 s[2:3], exec
	v_readlane_b32 s4, v253, 2
	v_readlane_b32 s5, v253, 3
	s_and_b64 s[4:5], s[2:3], s[4:5]
	s_mov_b64 exec, s[4:5]
	s_cbranch_execz .LBB0_940
	s_waitcnt vmcnt(0) expcnt(0) lgkmcnt(0)
	ds_read_b32 v2, v217
	ds_read_b32 v0, v218
	s_waitcnt lgkmcnt(1)
	v_cmp_ne_u32_e32 vcc, 0, v2
	s_cbranch_vccnz .LBB0_904
	v_readlane_b32 s6, v253, 6
	v_readlane_b32 s7, v253, 7
	s_load_dwordx2 s[4:5], s[6:7], 0x0
	s_nop 0
	s_load_dword s6, s[6:7], 0x8
	s_mov_b32 s13, 1
	s_waitcnt lgkmcnt(0)
	s_mul_i32 s12, s5, s4
	s_mul_i32 s12, s12, s6
	s_branch .LBB0_891
